# v38 + P0 silu-source loads batched + SGU LN-stat loads batched + P0 adaLN block rotation for load balance
# speedup vs baseline: 1.0207x; 1.0021x over previous
.LBB0_17:
	s_and_b64 vcc, exec, s[2:3]
	s_cbranch_vccz .LBB0_568
	s_movk_i32 s2, 0x1400
	v_cmp_gt_i32_e32 vcc, s2, v170
	s_and_saveexec_b64 s[2:3], vcc
	s_cbranch_execz .LBB0_25
	s_load_dwordx2 s[10:11], s[0:1], 0x8
	s_load_dwordx2 s[6:7], s[0:1], 0x18
	v_lshlrev_b32_e32 v2, 2, v170
	s_waitcnt vmcnt(0) lgkmcnt(0)
	global_load_dword v64, v2, s[10:11]
	global_load_dword v65, v2, s[10:11] offset:2048
	v_add_u32_e32 v3, 0x1000, v2
	global_load_dword v66, v3, s[10:11]
	global_load_dword v67, v3, s[10:11] offset:2048
	v_add_u32_e32 v3, 0x2000, v2
	global_load_dword v68, v3, s[10:11]
	global_load_dword v69, v3, s[10:11] offset:2048
	v_add_u32_e32 v3, 0x3000, v2
	global_load_dword v70, v3, s[10:11]
	global_load_dword v71, v3, s[10:11] offset:2048
	global_load_dword v72, v2, s[6:7]
	global_load_dword v73, v2, s[6:7] offset:2048
	v_lshl_add_u32 v6, v170, 2, 0
	s_waitcnt vmcnt(9)
	v_mul_f32_e32 v4, 0xbfb8aa3b, v64
	v_exp_f32_e32 v4, v4
	s_nop 0
	v_add_f32_e32 v4, 1.0, v4
	v_rcp_f32_e32 v4, v4
	s_nop 0
	v_mul_f32_e32 v0, v64, v4
	ds_write_b32 v6, v0
	s_waitcnt vmcnt(8)
	v_mul_f32_e32 v4, 0xbfb8aa3b, v65
	v_exp_f32_e32 v4, v4
	s_nop 0
	v_add_f32_e32 v4, 1.0, v4
	v_rcp_f32_e32 v4, v4
	s_nop 0
	v_mul_f32_e32 v0, v65, v4
	ds_write_b32 v6, v0 offset:2048
	s_waitcnt vmcnt(7)
	v_mul_f32_e32 v4, 0xbfb8aa3b, v66
	v_exp_f32_e32 v4, v4
	s_nop 0
	v_add_f32_e32 v4, 1.0, v4
	v_rcp_f32_e32 v4, v4
	s_nop 0
	v_mul_f32_e32 v0, v66, v4
	ds_write_b32 v6, v0 offset:4096
	s_waitcnt vmcnt(6)
	v_mul_f32_e32 v4, 0xbfb8aa3b, v67
	v_exp_f32_e32 v4, v4
	s_nop 0
	v_add_f32_e32 v4, 1.0, v4
	v_rcp_f32_e32 v4, v4
	s_nop 0
	v_mul_f32_e32 v0, v67, v4
	ds_write_b32 v6, v0 offset:6144
	s_waitcnt vmcnt(5)
	v_mul_f32_e32 v4, 0xbfb8aa3b, v68
	v_exp_f32_e32 v4, v4
	s_nop 0
	v_add_f32_e32 v4, 1.0, v4
	v_rcp_f32_e32 v4, v4
	s_nop 0
	v_mul_f32_e32 v0, v68, v4
	ds_write_b32 v6, v0 offset:8192
	s_waitcnt vmcnt(4)
	v_mul_f32_e32 v4, 0xbfb8aa3b, v69
	v_exp_f32_e32 v4, v4
	s_nop 0
	v_add_f32_e32 v4, 1.0, v4
	v_rcp_f32_e32 v4, v4
	s_nop 0
	v_mul_f32_e32 v0, v69, v4
	ds_write_b32 v6, v0 offset:10240
	s_waitcnt vmcnt(3)
	v_mul_f32_e32 v4, 0xbfb8aa3b, v70
	v_exp_f32_e32 v4, v4
	s_nop 0
	v_add_f32_e32 v4, 1.0, v4
	v_rcp_f32_e32 v4, v4
	s_nop 0
	v_mul_f32_e32 v0, v70, v4
	ds_write_b32 v6, v0 offset:12288
	s_waitcnt vmcnt(2)
	v_mul_f32_e32 v4, 0xbfb8aa3b, v71
	v_exp_f32_e32 v4, v4
	s_nop 0
	v_add_f32_e32 v4, 1.0, v4
	v_rcp_f32_e32 v4, v4
	s_nop 0
	v_mul_f32_e32 v0, v71, v4
	ds_write_b32 v6, v0 offset:14336
	s_waitcnt vmcnt(1)
	v_mul_f32_e32 v4, 0xbfb8aa3b, v72
	v_exp_f32_e32 v4, v4
	s_nop 0
	v_add_f32_e32 v4, 1.0, v4
	v_rcp_f32_e32 v4, v4
	s_nop 0
	v_mul_f32_e32 v0, v72, v4
	ds_write_b32 v6, v0 offset:16384
	s_waitcnt vmcnt(0)
	v_mul_f32_e32 v4, 0xbfb8aa3b, v73
	v_exp_f32_e32 v4, v4
	s_nop 0
	v_add_f32_e32 v4, 1.0, v4
	v_rcp_f32_e32 v4, v4
	s_nop 0
	v_mul_f32_e32 v0, v73, v4
	ds_write_b32 v6, v0 offset:18432

.LBB0_33:
	s_cmpk_lt_i32 s60, 0x400
	s_cbranch_scc1 .Lp0_norot
	s_addk_i32 s84, 0x200
	s_cmp_ge_i32 s84, s60
	s_cselect_b32 s2, s60, 0
	s_sub_i32 s84, s84, s2

.LBB0_246:
	s_ashr_i32 s3, s2, 31
	s_cmpk_gt_i32 s2, 0x1ff
	s_mov_b64 s[6:7], -1
	s_cbranch_scc0 .LBB0_252
	s_lshl_b32 s6, s2, 3
	s_and_b32 s6, s6, 56
	s_bfe_u32 s7, s2, 0x30005
	s_or_b32 s6, s6, s7
	s_add_i32 s8, s2, 0xfffffe00
	s_lshl_b32 s6, s6, 2
	s_and_b32 s7, s8, 0xffffff00
	s_or_b32 s6, s6, s7
	s_bfe_u32 s7, s2, 0x20003
	s_or_b32 s9, s6, s7
	s_cmpk_lt_u32 s2, 0x400
	v_readlane_b32 s10, v253, 8
	s_cselect_b64 s[6:7], -1, 0
	v_readlane_b32 s11, v253, 9
	s_and_b64 s[6:7], s[10:11], s[6:7]
	s_and_b64 s[6:7], s[6:7], exec
	s_cselect_b32 s10, s9, s8
	s_waitcnt vmcnt(0)
	v_mov_b32_e32 v68, v208
	s_lshl_b32 s6, s10, 5
	s_load_dwordx2 s[8:9], s[0:1], 0xa8
	s_and_b32 s14, s10, 3
	s_and_b32 s11, s6, 0x7f80
	v_readlane_b32 s6, v255, 36
	s_or_b32 s6, s14, s6
	s_ashr_i32 s7, s6, 31
	s_lshl_b64 s[12:13], s[6:7], 16
	v_lshlrev_b32_e32 v0, 3, v68
	s_waitcnt lgkmcnt(0)
	s_add_u32 s8, s8, s12
	v_and_b32_e32 v73, 0x78, v0
	v_ashrrev_i32_e32 v74, 4, v68
	s_addc_u32 s9, s9, s13
	v_lshlrev_b32_e32 v0, 2, v73
	v_lshlrev_b32_e32 v4, 7, v74
	v_lshl_add_u64 v[2:3], s[8:9], 0, v[0:1]
	v_ashrrev_i32_e32 v5, 31, v4
	v_lshl_add_u64 v[4:5], v[4:5], 2, v[2:3]
	global_load_dwordx4 v[18:21], v[4:5], off offset:16
	global_load_dwordx4 v[22:25], v[4:5], off
	v_add_u32_e32 v4, s11, v74
	v_ashrrev_i32_e32 v5, 31, v4
	v_readlane_b32 s8, v255, 41
	v_lshlrev_b64 v[4:5], 11, v[4:5]
	v_readlane_b32 s9, v255, 42
	s_lshl_b32 s20, s14, 8
	v_lshlrev_b32_e32 v50, 1, v73
	v_lshl_add_u64 v[4:5], s[8:9], 0, v[4:5]
	v_lshl_add_u64 v[4:5], v[4:5], 0, s[20:21]
	v_mov_b32_e32 v51, v1
	v_lshl_add_u64 v[4:5], v[4:5], 0, v[50:51]
	global_load_dwordx4 v[14:17], v[4:5], off offset:1024
	v_add_u32_e32 v4, 0x200, v68
	v_ashrrev_i32_e32 v71, 4, v4
	v_lshlrev_b32_e32 v4, 7, v71
	v_ashrrev_i32_e32 v5, 31, v4
	v_lshl_add_u64 v[4:5], v[4:5], 2, v[2:3]
	global_load_dwordx4 v[26:29], v[4:5], off offset:16
	global_load_dwordx4 v[30:33], v[4:5], off
	v_add_u32_e32 v4, s11, v71
	v_ashrrev_i32_e32 v5, 31, v4
	v_lshlrev_b64 v[4:5], 11, v[4:5]
	v_lshl_add_u64 v[4:5], s[8:9], 0, v[4:5]
	v_lshl_add_u64 v[4:5], v[4:5], 0, s[20:21]
	v_lshl_add_u64 v[4:5], v[4:5], 0, v[50:51]
	global_load_dwordx4 v[10:13], v[4:5], off offset:1024
	v_add_u32_e32 v4, 0x400, v68
	v_ashrrev_i32_e32 v70, 4, v4
	v_lshlrev_b32_e32 v4, 7, v70
	v_ashrrev_i32_e32 v5, 31, v4
	v_lshl_add_u64 v[4:5], v[4:5], 2, v[2:3]
	global_load_dwordx4 v[34:37], v[4:5], off offset:16
	global_load_dwordx4 v[38:41], v[4:5], off
	v_add_u32_e32 v4, s11, v70
	v_ashrrev_i32_e32 v5, 31, v4
	v_lshlrev_b64 v[4:5], 11, v[4:5]
	v_lshl_add_u64 v[4:5], s[8:9], 0, v[4:5]
	v_lshl_add_u64 v[4:5], v[4:5], 0, s[20:21]
	v_lshl_add_u64 v[4:5], v[4:5], 0, v[50:51]
	global_load_dwordx4 v[6:9], v[4:5], off offset:1024
	v_add_u32_e32 v4, 0x600, v68
	v_ashrrev_i32_e32 v69, 4, v4
	v_lshlrev_b32_e32 v4, 7, v69
	v_ashrrev_i32_e32 v5, 31, v4
	v_lshl_add_u64 v[2:3], v[4:5], 2, v[2:3]
	global_load_dwordx4 v[42:45], v[2:3], off offset:16
	global_load_dwordx4 v[46:49], v[2:3], off
	v_add_u32_e32 v2, s11, v69
	v_ashrrev_i32_e32 v3, 31, v2
	v_lshlrev_b64 v[2:3], 11, v[2:3]
	v_lshl_add_u64 v[2:3], s[8:9], 0, v[2:3]
	v_lshl_add_u64 v[2:3], v[2:3], 0, s[20:21]
	v_ashrrev_i32_e32 v72, 2, v68
	v_lshl_add_u64 v[2:3], v[2:3], 0, v[50:51]
	v_add_u32_e32 v50, s11, v72
	v_ashrrev_i32_e32 v51, 31, v50
	v_and_b32_e32 v75, 3, v68
	v_lshlrev_b64 v[50:51], 11, v[50:51]
	v_lshl_add_u64 v[50:51], s[8:9], 0, v[50:51]
	v_lshlrev_b32_e32 v52, 8, v75
	v_mov_b32_e32 v53, v1
	v_lshl_add_u64 v[66:67], v[50:51], 0, v[52:53]
	global_load_dwordx4 v[2:5], v[2:3], off offset:1024
	s_nop 0
	global_load_dwordx4 v[80:83], v[66:67], off offset:1072
	global_load_dwordx4 v[84:87], v[66:67], off offset:1056
	global_load_dwordx4 v[88:91], v[66:67], off offset:1040
	global_load_dwordx4 v[92:95], v[66:67], off offset:1024
	global_load_dwordx4 v[96:99], v[66:67], off offset:1136
	global_load_dwordx4 v[100:103], v[66:67], off offset:1120
	global_load_dwordx4 v[104:107], v[66:67], off offset:1104
	global_load_dwordx4 v[108:111], v[66:67], off offset:1088
	global_load_dwordx4 v[112:115], v[66:67], off offset:1200
	global_load_dwordx4 v[116:119], v[66:67], off offset:1184
	global_load_dwordx4 v[120:123], v[66:67], off offset:1168
	global_load_dwordx4 v[124:127], v[66:67], off offset:1152
	global_load_dwordx4 v[128:131], v[66:67], off offset:1264
	global_load_dwordx4 v[132:135], v[66:67], off offset:1248
	global_load_dwordx4 v[136:139], v[66:67], off offset:1232
	global_load_dwordx4 v[140:143], v[66:67], off offset:1216
	v_cmp_lt_i32_e32 vcc, v221, v220
	s_lshl_b32 s7, s14, 7
	s_waitcnt vmcnt(12)
	v_lshlrev_b32_e32 v76, 16, v92
	v_and_b32_e32 v92, 0xffff0000, v92
	v_add_f32_e32 v77, v76, v92
	v_mul_f32_e32 v92, v92, v92
	v_fmac_f32_e32 v92, v76, v76
	v_lshlrev_b32_e32 v76, 16, v93
	v_and_b32_e32 v93, 0xffff0000, v93
	v_add_f32_e32 v78, v76, v93
	v_mul_f32_e32 v93, v93, v93
	v_fmac_f32_e32 v93, v76, v76
	v_add_f32_e32 v92, v92, v93
	v_lshlrev_b32_e32 v93, 16, v94
	v_and_b32_e32 v94, 0xffff0000, v94
	v_add_f32_e32 v76, v93, v94
	v_mul_f32_e32 v94, v94, v94
	v_fmac_f32_e32 v94, v93, v93
	v_add_f32_e32 v92, v94, v92
	v_lshlrev_b32_e32 v93, 16, v95
	v_and_b32_e32 v94, 0xffff0000, v95
	v_add_f32_e32 v95, v93, v94
	v_mul_f32_e32 v94, v94, v94
	v_fmac_f32_e32 v94, v93, v93
	v_lshlrev_b32_e32 v93, 16, v88
	v_and_b32_e32 v88, 0xffff0000, v88
	v_add_f32_e32 v92, v94, v92
	v_add_f32_e32 v94, v93, v88
	v_mul_f32_e32 v88, v88, v88
	v_fmac_f32_e32 v88, v93, v93
	v_add_f32_e32 v88, v88, v92
	v_lshlrev_b32_e32 v92, 16, v89
	v_and_b32_e32 v89, 0xffff0000, v89
	v_add_f32_e32 v93, v92, v89
	v_mul_f32_e32 v89, v89, v89
	v_fmac_f32_e32 v89, v92, v92
	v_add_f32_e32 v88, v89, v88
	v_lshlrev_b32_e32 v89, 16, v90
	v_and_b32_e32 v90, 0xffff0000, v90
	v_add_f32_e32 v92, v89, v90
	v_mul_f32_e32 v90, v90, v90
	v_fmac_f32_e32 v90, v89, v89
	v_add_f32_e32 v88, v90, v88
	v_lshlrev_b32_e32 v89, 16, v91
	v_and_b32_e32 v90, 0xffff0000, v91
	v_add_f32_e32 v91, v89, v90
	v_mul_f32_e32 v90, v90, v90
	v_fmac_f32_e32 v90, v89, v89
	v_lshlrev_b32_e32 v89, 16, v84
	v_and_b32_e32 v84, 0xffff0000, v84
	v_add_f32_e32 v88, v90, v88
	v_add_f32_e32 v90, v89, v84
	v_mul_f32_e32 v84, v84, v84
	v_fmac_f32_e32 v84, v89, v89
	v_add_f32_e32 v84, v84, v88
	v_lshlrev_b32_e32 v88, 16, v85
	v_and_b32_e32 v85, 0xffff0000, v85
	v_add_f32_e32 v89, v88, v85
	v_mul_f32_e32 v85, v85, v85
	v_fmac_f32_e32 v85, v88, v88
	v_add_f32_e32 v84, v85, v84
	v_lshlrev_b32_e32 v85, 16, v86
	v_and_b32_e32 v86, 0xffff0000, v86
	v_add_f32_e32 v88, v85, v86
	v_mul_f32_e32 v86, v86, v86
	v_add_f32_e32 v77, 0, v77
	v_fmac_f32_e32 v86, v85, v85
	v_add_f32_e32 v77, v78, v77
	v_add_f32_e32 v84, v86, v84
	v_lshlrev_b32_e32 v85, 16, v87
	v_and_b32_e32 v86, 0xffff0000, v87
	v_add_f32_e32 v76, v76, v77
	v_add_f32_e32 v87, v85, v86
	v_mul_f32_e32 v86, v86, v86
	v_add_f32_e32 v95, v95, v76
	v_fmac_f32_e32 v86, v85, v85
	v_lshlrev_b32_e32 v85, 16, v80
	v_and_b32_e32 v80, 0xffff0000, v80
	v_add_f32_e32 v94, v94, v95
	v_add_f32_e32 v84, v86, v84
	v_add_f32_e32 v86, v85, v80
	v_mul_f32_e32 v80, v80, v80
	v_add_f32_e32 v93, v93, v94
	v_fmac_f32_e32 v80, v85, v85
	v_add_f32_e32 v92, v92, v93
	v_add_f32_e32 v80, v80, v84
	v_lshlrev_b32_e32 v84, 16, v81
	v_and_b32_e32 v81, 0xffff0000, v81
	v_add_f32_e32 v91, v91, v92
	v_add_f32_e32 v85, v84, v81
	v_mul_f32_e32 v81, v81, v81
	v_add_f32_e32 v90, v90, v91
	v_fmac_f32_e32 v81, v84, v84
	v_add_f32_e32 v89, v89, v90
	v_add_f32_e32 v80, v81, v80
	v_lshlrev_b32_e32 v81, 16, v82
	v_and_b32_e32 v82, 0xffff0000, v82
	v_add_f32_e32 v88, v88, v89
	v_add_f32_e32 v84, v81, v82
	v_mul_f32_e32 v82, v82, v82
	v_add_f32_e32 v87, v87, v88
	v_fmac_f32_e32 v82, v81, v81
	v_add_f32_e32 v86, v86, v87
	v_add_f32_e32 v80, v82, v80
	v_lshlrev_b32_e32 v81, 16, v83
	v_and_b32_e32 v82, 0xffff0000, v83
	v_add_f32_e32 v85, v85, v86
	v_add_f32_e32 v83, v81, v82
	v_mul_f32_e32 v82, v82, v82
	v_add_f32_e32 v84, v84, v85
	v_fmac_f32_e32 v82, v81, v81
	v_add_f32_e32 v77, v83, v84
	v_add_f32_e32 v76, v82, v80
	s_waitcnt vmcnt(8)
	v_lshlrev_b32_e32 v78, 16, v108
	v_and_b32_e32 v108, 0xffff0000, v108
	v_add_f32_e32 v79, v78, v108
	v_mul_f32_e32 v108, v108, v108
	v_fmac_f32_e32 v108, v78, v78
	v_add_f32_e32 v108, v108, v76
	v_lshlrev_b32_e32 v76, 16, v109
	v_and_b32_e32 v109, 0xffff0000, v109
	v_add_f32_e32 v78, v76, v109
	v_mul_f32_e32 v109, v109, v109
	v_fmac_f32_e32 v109, v76, v76
	v_add_f32_e32 v108, v109, v108
	v_lshlrev_b32_e32 v109, 16, v110
	v_and_b32_e32 v110, 0xffff0000, v110
	v_add_f32_e32 v76, v109, v110
	v_mul_f32_e32 v110, v110, v110
	v_fmac_f32_e32 v110, v109, v109
	v_add_f32_e32 v108, v110, v108
	v_lshlrev_b32_e32 v109, 16, v111
	v_and_b32_e32 v110, 0xffff0000, v111
	v_add_f32_e32 v111, v109, v110
	v_mul_f32_e32 v110, v110, v110
	v_fmac_f32_e32 v110, v109, v109
	v_lshlrev_b32_e32 v109, 16, v104
	v_and_b32_e32 v104, 0xffff0000, v104
	v_add_f32_e32 v108, v110, v108
	v_add_f32_e32 v110, v109, v104
	v_mul_f32_e32 v104, v104, v104
	v_fmac_f32_e32 v104, v109, v109
	v_add_f32_e32 v104, v104, v108
	v_lshlrev_b32_e32 v108, 16, v105
	v_and_b32_e32 v105, 0xffff0000, v105
	v_add_f32_e32 v109, v108, v105
	v_mul_f32_e32 v105, v105, v105
	v_fmac_f32_e32 v105, v108, v108
	v_add_f32_e32 v104, v105, v104
	v_lshlrev_b32_e32 v105, 16, v106
	v_and_b32_e32 v106, 0xffff0000, v106
	v_add_f32_e32 v108, v105, v106
	v_mul_f32_e32 v106, v106, v106
	v_fmac_f32_e32 v106, v105, v105
	v_add_f32_e32 v104, v106, v104
	v_lshlrev_b32_e32 v105, 16, v107
	v_and_b32_e32 v106, 0xffff0000, v107
	v_add_f32_e32 v107, v105, v106
	v_mul_f32_e32 v106, v106, v106
	v_fmac_f32_e32 v106, v105, v105
	v_lshlrev_b32_e32 v105, 16, v100
	v_and_b32_e32 v100, 0xffff0000, v100
	v_add_f32_e32 v104, v106, v104
	v_add_f32_e32 v106, v105, v100
	v_mul_f32_e32 v100, v100, v100
	v_fmac_f32_e32 v100, v105, v105
	v_add_f32_e32 v100, v100, v104
	v_lshlrev_b32_e32 v104, 16, v101
	v_and_b32_e32 v101, 0xffff0000, v101
	v_add_f32_e32 v105, v104, v101
	v_mul_f32_e32 v101, v101, v101
	v_fmac_f32_e32 v101, v104, v104
	v_add_f32_e32 v100, v101, v100
	v_lshlrev_b32_e32 v101, 16, v102
	v_and_b32_e32 v102, 0xffff0000, v102
	v_add_f32_e32 v104, v101, v102
	v_mul_f32_e32 v102, v102, v102
	v_add_f32_e32 v77, v79, v77
	v_fmac_f32_e32 v102, v101, v101
	v_add_f32_e32 v77, v78, v77
	v_add_f32_e32 v100, v102, v100
	v_lshlrev_b32_e32 v101, 16, v103
	v_and_b32_e32 v102, 0xffff0000, v103
	v_add_f32_e32 v76, v76, v77
	v_add_f32_e32 v103, v101, v102
	v_mul_f32_e32 v102, v102, v102
	v_add_f32_e32 v111, v111, v76
	v_fmac_f32_e32 v102, v101, v101
	v_lshlrev_b32_e32 v101, 16, v96
	v_and_b32_e32 v96, 0xffff0000, v96
	v_add_f32_e32 v110, v110, v111
	v_add_f32_e32 v100, v102, v100
	v_add_f32_e32 v102, v101, v96
	v_mul_f32_e32 v96, v96, v96
	v_add_f32_e32 v109, v109, v110
	v_fmac_f32_e32 v96, v101, v101
	v_add_f32_e32 v108, v108, v109
	v_add_f32_e32 v96, v96, v100
	v_lshlrev_b32_e32 v100, 16, v97
	v_and_b32_e32 v97, 0xffff0000, v97
	v_add_f32_e32 v107, v107, v108
	v_add_f32_e32 v101, v100, v97
	v_mul_f32_e32 v97, v97, v97
	v_add_f32_e32 v106, v106, v107
	v_fmac_f32_e32 v97, v100, v100
	v_add_f32_e32 v105, v105, v106
	v_add_f32_e32 v96, v97, v96
	v_lshlrev_b32_e32 v97, 16, v98
	v_and_b32_e32 v98, 0xffff0000, v98
	v_add_f32_e32 v104, v104, v105
	v_add_f32_e32 v100, v97, v98
	v_mul_f32_e32 v98, v98, v98
	v_add_f32_e32 v103, v103, v104
	v_fmac_f32_e32 v98, v97, v97
	v_add_f32_e32 v102, v102, v103
	v_add_f32_e32 v96, v98, v96
	v_lshlrev_b32_e32 v97, 16, v99
	v_and_b32_e32 v98, 0xffff0000, v99
	v_add_f32_e32 v101, v101, v102
	v_add_f32_e32 v99, v97, v98
	v_mul_f32_e32 v98, v98, v98
	v_add_f32_e32 v100, v100, v101
	v_fmac_f32_e32 v98, v97, v97
	v_add_f32_e32 v77, v99, v100
	v_add_f32_e32 v76, v98, v96
	s_waitcnt vmcnt(4)
	v_lshlrev_b32_e32 v78, 16, v124
	v_and_b32_e32 v124, 0xffff0000, v124
	v_add_f32_e32 v79, v78, v124
	v_mul_f32_e32 v124, v124, v124
	v_fmac_f32_e32 v124, v78, v78
	v_add_f32_e32 v124, v124, v76
	v_lshlrev_b32_e32 v76, 16, v125
	v_and_b32_e32 v125, 0xffff0000, v125
	v_add_f32_e32 v78, v76, v125
	v_mul_f32_e32 v125, v125, v125
	v_fmac_f32_e32 v125, v76, v76
	v_add_f32_e32 v124, v125, v124
	v_lshlrev_b32_e32 v125, 16, v126
	v_and_b32_e32 v126, 0xffff0000, v126
	v_add_f32_e32 v76, v125, v126
	v_mul_f32_e32 v126, v126, v126
	v_fmac_f32_e32 v126, v125, v125
	v_add_f32_e32 v124, v126, v124
	v_lshlrev_b32_e32 v125, 16, v127
	v_and_b32_e32 v126, 0xffff0000, v127
	v_add_f32_e32 v127, v125, v126
	v_mul_f32_e32 v126, v126, v126
	v_fmac_f32_e32 v126, v125, v125
	v_lshlrev_b32_e32 v125, 16, v120
	v_and_b32_e32 v120, 0xffff0000, v120
	v_add_f32_e32 v124, v126, v124
	v_add_f32_e32 v126, v125, v120
	v_mul_f32_e32 v120, v120, v120
	v_fmac_f32_e32 v120, v125, v125
	v_add_f32_e32 v120, v120, v124
	v_lshlrev_b32_e32 v124, 16, v121
	v_and_b32_e32 v121, 0xffff0000, v121
	v_add_f32_e32 v125, v124, v121
	v_mul_f32_e32 v121, v121, v121
	v_fmac_f32_e32 v121, v124, v124
	v_add_f32_e32 v120, v121, v120
	v_lshlrev_b32_e32 v121, 16, v122
	v_and_b32_e32 v122, 0xffff0000, v122
	v_add_f32_e32 v124, v121, v122
	v_mul_f32_e32 v122, v122, v122
	v_fmac_f32_e32 v122, v121, v121
	v_add_f32_e32 v120, v122, v120
	v_lshlrev_b32_e32 v121, 16, v123
	v_and_b32_e32 v122, 0xffff0000, v123
	v_add_f32_e32 v123, v121, v122
	v_mul_f32_e32 v122, v122, v122
	v_fmac_f32_e32 v122, v121, v121
	v_lshlrev_b32_e32 v121, 16, v116
	v_and_b32_e32 v116, 0xffff0000, v116
	v_add_f32_e32 v120, v122, v120
	v_add_f32_e32 v122, v121, v116
	v_mul_f32_e32 v116, v116, v116
	v_fmac_f32_e32 v116, v121, v121
	v_add_f32_e32 v116, v116, v120
	v_lshlrev_b32_e32 v120, 16, v117
	v_and_b32_e32 v117, 0xffff0000, v117
	v_add_f32_e32 v121, v120, v117
	v_mul_f32_e32 v117, v117, v117
	v_fmac_f32_e32 v117, v120, v120
	v_add_f32_e32 v116, v117, v116
	v_lshlrev_b32_e32 v117, 16, v118
	v_and_b32_e32 v118, 0xffff0000, v118
	v_add_f32_e32 v120, v117, v118
	v_mul_f32_e32 v118, v118, v118
	v_add_f32_e32 v77, v79, v77
	v_fmac_f32_e32 v118, v117, v117
	v_add_f32_e32 v77, v78, v77
	v_add_f32_e32 v116, v118, v116
	v_lshlrev_b32_e32 v117, 16, v119
	v_and_b32_e32 v118, 0xffff0000, v119
	v_add_f32_e32 v76, v76, v77
	v_add_f32_e32 v119, v117, v118
	v_mul_f32_e32 v118, v118, v118
	v_add_f32_e32 v127, v127, v76
	v_fmac_f32_e32 v118, v117, v117
	v_lshlrev_b32_e32 v117, 16, v112
	v_and_b32_e32 v112, 0xffff0000, v112
	v_add_f32_e32 v126, v126, v127
	v_add_f32_e32 v116, v118, v116
	v_add_f32_e32 v118, v117, v112
	v_mul_f32_e32 v112, v112, v112
	v_add_f32_e32 v125, v125, v126
	v_fmac_f32_e32 v112, v117, v117
	v_add_f32_e32 v124, v124, v125
	v_add_f32_e32 v112, v112, v116
	v_lshlrev_b32_e32 v116, 16, v113
	v_and_b32_e32 v113, 0xffff0000, v113
	v_add_f32_e32 v123, v123, v124
	v_add_f32_e32 v117, v116, v113
	v_mul_f32_e32 v113, v113, v113
	v_add_f32_e32 v122, v122, v123
	v_fmac_f32_e32 v113, v116, v116
	v_add_f32_e32 v121, v121, v122
	v_add_f32_e32 v112, v113, v112
	v_lshlrev_b32_e32 v113, 16, v114
	v_and_b32_e32 v114, 0xffff0000, v114
	v_add_f32_e32 v120, v120, v121
	v_add_f32_e32 v116, v113, v114
	v_mul_f32_e32 v114, v114, v114
	v_add_f32_e32 v119, v119, v120
	v_fmac_f32_e32 v114, v113, v113
	v_add_f32_e32 v118, v118, v119
	v_add_f32_e32 v112, v114, v112
	v_lshlrev_b32_e32 v113, 16, v115
	v_and_b32_e32 v114, 0xffff0000, v115
	v_add_f32_e32 v117, v117, v118
	v_add_f32_e32 v115, v113, v114
	v_mul_f32_e32 v114, v114, v114
	v_add_f32_e32 v116, v116, v117
	v_fmac_f32_e32 v114, v113, v113
	v_add_f32_e32 v77, v115, v116
	v_add_f32_e32 v76, v114, v112
	s_waitcnt vmcnt(0)
	v_lshlrev_b32_e32 v66, 16, v140
	v_and_b32_e32 v140, 0xffff0000, v140
	v_add_f32_e32 v67, v66, v140
	v_mul_f32_e32 v140, v140, v140
	v_fmac_f32_e32 v140, v66, v66
	v_lshlrev_b32_e32 v66, 16, v141
	v_and_b32_e32 v141, 0xffff0000, v141
	v_add_f32_e32 v140, v140, v76
	v_add_f32_e32 v76, v66, v141
	v_mul_f32_e32 v141, v141, v141
	v_fmac_f32_e32 v141, v66, v66
	v_add_f32_e32 v140, v141, v140
	v_lshlrev_b32_e32 v141, 16, v142
	v_and_b32_e32 v142, 0xffff0000, v142
	v_add_f32_e32 v66, v141, v142
	v_mul_f32_e32 v142, v142, v142
	v_fmac_f32_e32 v142, v141, v141
	v_add_f32_e32 v140, v142, v140
	v_lshlrev_b32_e32 v141, 16, v143
	v_and_b32_e32 v142, 0xffff0000, v143
	v_add_f32_e32 v143, v141, v142
	v_mul_f32_e32 v142, v142, v142
	v_fmac_f32_e32 v142, v141, v141
	v_lshlrev_b32_e32 v141, 16, v136
	v_and_b32_e32 v136, 0xffff0000, v136
	v_add_f32_e32 v140, v142, v140
	v_add_f32_e32 v142, v141, v136
	v_mul_f32_e32 v136, v136, v136
	v_fmac_f32_e32 v136, v141, v141
	v_add_f32_e32 v136, v136, v140
	v_lshlrev_b32_e32 v140, 16, v137
	v_and_b32_e32 v137, 0xffff0000, v137
	v_add_f32_e32 v141, v140, v137
	v_mul_f32_e32 v137, v137, v137
	v_fmac_f32_e32 v137, v140, v140
	v_add_f32_e32 v136, v137, v136
	v_lshlrev_b32_e32 v137, 16, v138
	v_and_b32_e32 v138, 0xffff0000, v138
	v_add_f32_e32 v140, v137, v138
	v_mul_f32_e32 v138, v138, v138
	v_fmac_f32_e32 v138, v137, v137
	v_add_f32_e32 v136, v138, v136
	v_lshlrev_b32_e32 v137, 16, v139
	v_and_b32_e32 v138, 0xffff0000, v139
	v_add_f32_e32 v139, v137, v138
	v_mul_f32_e32 v138, v138, v138
	v_fmac_f32_e32 v138, v137, v137
	v_lshlrev_b32_e32 v137, 16, v132
	v_and_b32_e32 v132, 0xffff0000, v132
	v_add_f32_e32 v136, v138, v136
	v_add_f32_e32 v138, v137, v132
	v_mul_f32_e32 v132, v132, v132
	v_fmac_f32_e32 v132, v137, v137
	v_add_f32_e32 v132, v132, v136
	v_lshlrev_b32_e32 v136, 16, v133
	v_and_b32_e32 v133, 0xffff0000, v133
	v_add_f32_e32 v137, v136, v133
	v_mul_f32_e32 v133, v133, v133
	v_fmac_f32_e32 v133, v136, v136
	v_add_f32_e32 v132, v133, v132
	v_lshlrev_b32_e32 v133, 16, v134
	v_and_b32_e32 v134, 0xffff0000, v134
	v_add_f32_e32 v136, v133, v134
	v_mul_f32_e32 v134, v134, v134
	v_fmac_f32_e32 v134, v133, v133
	v_add_f32_e32 v67, v67, v77
	v_add_f32_e32 v132, v134, v132
	v_lshlrev_b32_e32 v133, 16, v135
	v_and_b32_e32 v134, 0xffff0000, v135
	v_add_f32_e32 v67, v76, v67
	v_add_f32_e32 v135, v133, v134
	v_mul_f32_e32 v134, v134, v134
	v_add_f32_e32 v66, v66, v67
	v_fmac_f32_e32 v134, v133, v133
	v_lshlrev_b32_e32 v133, 16, v128
	v_and_b32_e32 v128, 0xffff0000, v128
	v_add_f32_e32 v143, v143, v66
	v_add_f32_e32 v132, v134, v132
	v_add_f32_e32 v134, v133, v128
	v_mul_f32_e32 v128, v128, v128
	v_add_f32_e32 v142, v142, v143
	v_fmac_f32_e32 v128, v133, v133
	v_add_f32_e32 v141, v141, v142
	v_add_f32_e32 v128, v128, v132
	v_lshlrev_b32_e32 v132, 16, v129
	v_and_b32_e32 v129, 0xffff0000, v129
	v_add_f32_e32 v140, v140, v141
	v_add_f32_e32 v133, v132, v129
	v_mul_f32_e32 v129, v129, v129
	v_add_f32_e32 v139, v139, v140
	v_fmac_f32_e32 v129, v132, v132
	v_add_f32_e32 v138, v138, v139
	v_add_f32_e32 v128, v129, v128
	v_lshlrev_b32_e32 v129, 16, v130
	v_and_b32_e32 v130, 0xffff0000, v130
	v_add_f32_e32 v137, v137, v138
	v_add_f32_e32 v132, v129, v130
	v_mul_f32_e32 v130, v130, v130
	v_add_f32_e32 v136, v136, v137
	v_fmac_f32_e32 v130, v129, v129
	v_add_f32_e32 v135, v135, v136
	v_add_f32_e32 v128, v130, v128
	v_lshlrev_b32_e32 v129, 16, v131
	v_and_b32_e32 v130, 0xffff0000, v131
	v_add_f32_e32 v134, v134, v135
	v_add_f32_e32 v131, v129, v130
	v_mul_f32_e32 v130, v130, v130
	v_add_f32_e32 v133, v133, v134
	v_fmac_f32_e32 v130, v129, v129
	v_add_f32_e32 v132, v132, v133
	v_add_f32_e32 v130, v130, v128
	v_cndmask_b32_e32 v128, v218, v221, vcc
	v_add_f32_e32 v131, v131, v132
	v_lshlrev_b32_e32 v132, 2, v128
	ds_bpermute_b32 v128, v132, v131
	ds_bpermute_b32 v132, v132, v130
	v_cmp_lt_i32_e32 vcc, v222, v220
	s_waitcnt lgkmcnt(1)
	v_add_f32_e32 v128, v131, v128
	v_cndmask_b32_e32 v129, v218, v222, vcc
	v_lshlrev_b32_e32 v131, 2, v129
	s_waitcnt lgkmcnt(0)
	v_add_f32_e32 v130, v130, v132
	ds_bpermute_b32 v129, v131, v128
	ds_bpermute_b32 v131, v131, v130
	v_cmp_eq_u32_e32 vcc, 0, v75
	s_and_saveexec_b64 s[8:9], vcc
	s_cbranch_execz .LBB0_249
	s_waitcnt lgkmcnt(1)
	v_add_f32_e32 v128, v128, v129
	v_mul_f32_e32 v128, 0x3b000000, v128
	s_waitcnt lgkmcnt(0)
	v_add_f32_e32 v130, v130, v131
	v_mul_f32_e32 v129, v128, v128
	s_mov_b32 s12, 0x3b000000
	v_fma_f32 v129, v130, s12, -v129
	v_max_f32_e32 v129, 0, v129
	v_add_f32_e32 v129, 0x358637bd, v129
	v_mul_f32_e32 v130, 0x4f800000, v129
	v_cmp_gt_f32_e32 vcc, s23, v129
	s_nop 1
	v_cndmask_b32_e32 v129, v129, v130, vcc
	v_sqrt_f32_e32 v130, v129
	s_nop 0
	v_add_u32_e32 v131, -1, v130
	v_fma_f32 v132, -v131, v130, v129
	v_cmp_ge_f32_e64 s[42:43], 0, v132
	v_add_u32_e32 v132, 1, v130
	s_nop 0
	v_cndmask_b32_e64 v131, v130, v131, s[42:43]
	v_fma_f32 v130, -v132, v130, v129
	v_cmp_lt_f32_e64 s[42:43], 0, v130
	s_nop 1
	v_cndmask_b32_e64 v130, v131, v132, s[42:43]
	v_mul_f32_e32 v131, 0x37800000, v130
	v_cndmask_b32_e32 v130, v130, v131, vcc
	v_cmp_class_f32_e32 vcc, v129, v210
	v_lshl_add_u32 v132, v72, 2, 0
	v_add_u32_e32 v132, 0x20000, v132
	v_cndmask_b32_e32 v129, v130, v129, vcc
	v_div_scale_f32 v130, s[12:13], v129, v129, 1.0
	v_rcp_f32_e32 v131, v130
	s_nop 0
	v_fma_f32 v133, -v130, v131, 1.0
	v_fmac_f32_e32 v131, v133, v131
	v_div_scale_f32 v133, vcc, 1.0, v129, 1.0
	v_mul_f32_e32 v134, v133, v131
	v_fma_f32 v135, -v130, v134, v133
	v_fmac_f32_e32 v134, v135, v131
	v_fma_f32 v130, -v130, v134, v133
	v_div_fmas_f32 v130, v130, v131, v134
	v_div_fixup_f32 v129, v130, v129, 1.0
	ds_write2st64_b32 v132, v128, v129 offset1:2
